# block attention loops: shorter row-max chain, persistent LDS fragment addresses shared by tile pairs, rescale threshold and bias kept in registers
# baseline (speedup 1.0000x reference)
_Z10fwd_kernel6Params:
	s_mov_b64 s[92:93], s[0:1]
	s_mov_b32 s100, 0
	s_add_u32 s0, s92, 0xc8
	s_load_dword s3, s[92:93], 0xc8
	s_addc_u32 s1, s93, 0
	v_and_b32_e32 v1, 0x3ff, v0
	v_writelane_b32 v254, s0, 0
	v_readfirstlane_b32 s31, v1
	v_cmp_eq_u32_e64 s[4:5], 0, v1
	v_writelane_b32 v254, s1, 1
	s_getreg_b32 s0, hwreg(HW_REG_XCC_ID, 0, 4)
	s_and_b32 s30, s0, 15
	s_mov_b64 s[0:1], exec
	v_writelane_b32 v254, s4, 2
	s_nop 1
	v_writelane_b32 v254, s5, 3
	s_and_b64 s[4:5], s[0:1], s[4:5]
	s_mov_b64 exec, s[4:5]
	s_cbranch_execz .LBB0_3
	s_add_i32 s6, 0, 0x20000
	v_mov_b32_e32 v2, 0
	v_mov_b32_e32 v3, s6
	s_add_i32 s6, 0, 0x20004
	s_mov_b64 s[4:5], exec
	ds_write_b32 v3, v2
	v_mov_b32_e32 v3, s6
	ds_write_b32 v3, v2
	v_mbcnt_lo_u32_b32 v2, s4, 0
	v_mbcnt_hi_u32_b32 v2, s5, v2
	v_cmp_eq_u32_e32 vcc, 0, v2
	s_and_b64 s[6:7], exec, vcc
	s_mov_b64 exec, s[6:7]
	s_cbranch_execz .LBB0_3
	s_load_dwordx2 s[6:7], s[92:93], 0x98
	s_lshl_b32 s8, s30, 8
	v_mov_b32_e32 v2, 0x1f3d0000
	s_waitcnt lgkmcnt(0)
	s_add_u32 s6, s6, s8
	s_addc_u32 s7, s7, 0
	s_bcnt1_i32_b64 s4, s[4:5]
	v_mov_b32_e32 v3, s4
	global_atomic_add v2, v3, s[6:7] offset:1024

.LBB0_548:
	s_add_i32 s98, s19, -1
	s_mul_hi_u32 s99, s98, 0x38e38e39
	s_lshr_b32 s99, s99, 1
	s_mul_i32 s40, s99, 9
	s_sub_i32 s98, s98, s40
	s_mov_b32 s40, 0x8
	s_bitcmp1_b32 s40, s98
	s_cbranch_scc0 .Lrep_no
	s_mov_b32 s40, 0xf
	s_bitcmp1_b32 s40, s99
	s_cbranch_scc0 .Lrep_no
	s_xor_b32 s100, s100, 1
	s_cmp_eq_u32 s100, 1
	s_cbranch_scc1 .LBB0_549
